# attention: QK K-frag read hoist + row-sum pk chains interleaved without nops + PV first V-frag reads hoisted (bit-exact)
# speedup vs baseline: 1.0038x; 1.0017x over previous
.LBB0_362:
	s_and_b32 s14, s11, 1
	s_mul_i32 s12, s14, 0x4600
	s_add_i32 s15, s12, 16
	v_add3_u32 v160, s15, v209, v214
	ds_read_b128 v[96:99], v160
	ds_read_b128 v[224:227], v160 offset:4608
	ds_read_b128 v[228:231], v160 offset:32
	ds_read_b128 v[232:235], v160 offset:4640
	ds_read_b128 v[240:243], v160 offset:64
	ds_read_b128 v[248:251], v160 offset:4672
	v_mov_b64_e32 v[126:127], v[62:63]
	v_mov_b64_e32 v[124:125], v[60:61]
	v_mov_b64_e32 v[122:123], v[58:59]
	s_waitcnt lgkmcnt(5)
	v_mfma_f32_32x32x16_bf16 v[144:159], v[96:99], v[162:165], v[48:63]
	v_mov_b64_e32 v[120:121], v[56:57]
	v_mov_b64_e32 v[118:119], v[54:55]
	v_mov_b64_e32 v[116:117], v[52:53]
	v_mov_b64_e32 v[114:115], v[50:51]
	v_mov_b64_e32 v[112:113], v[48:49]
	v_mfma_f32_32x32x16_bf16 v[128:143], v[96:99], v[166:169], v[80:95]
	v_mov_b64_e32 v[110:111], v[94:95]
	v_mov_b64_e32 v[108:109], v[92:93]
	v_mov_b64_e32 v[106:107], v[90:91]
	v_mov_b64_e32 v[104:105], v[88:89]
	v_mov_b64_e32 v[102:103], v[86:87]
	v_mov_b64_e32 v[100:101], v[84:85]
	v_mov_b64_e32 v[98:99], v[82:83]
	v_mov_b64_e32 v[96:97], v[80:81]
	s_waitcnt lgkmcnt(4)
	v_mfma_f32_32x32x16_bf16 v[112:127], v[224:227], v[162:165], v[112:127]
	s_nop 0
	v_mfma_f32_32x32x16_bf16 v[96:111], v[224:227], v[166:169], v[96:111]
	ds_read_b128 v[224:227], v160 offset:96
	s_waitcnt lgkmcnt(4)
	v_mfma_f32_32x32x16_bf16 v[144:159], v[228:231], v[170:173], v[144:159]
	s_waitcnt lgkmcnt(3)
	v_mfma_f32_32x32x16_bf16 v[112:127], v[232:235], v[170:173], v[112:127]
	v_mfma_f32_32x32x16_bf16 v[128:143], v[228:231], v[174:177], v[128:143]
	v_mfma_f32_32x32x16_bf16 v[96:111], v[232:235], v[174:177], v[96:111]
	ds_read_b128 v[228:231], v160 offset:4704
	s_waitcnt lgkmcnt(3)
	v_mfma_f32_32x32x16_bf16 v[144:159], v[240:243], v[178:181], v[144:159]
	s_waitcnt lgkmcnt(2)
	v_mfma_f32_32x32x16_bf16 v[112:127], v[248:251], v[178:181], v[112:127]
	v_mfma_f32_32x32x16_bf16 v[128:143], v[240:243], v[186:189], v[128:143]
	v_mfma_f32_32x32x16_bf16 v[96:111], v[248:251], v[186:189], v[96:111]
	v_add3_u32 v240, s15, v211, v210
	v_add_u32_e32 v241, 0x3000, v240
	v_add_u32_e32 v240, 0x2000, v240
	ds_read2_b64 v[232:235], v240 offset0:128 offset1:130
	ds_read2_b64 v[248:251], v241 offset0:160 offset1:162
	s_waitcnt lgkmcnt(3)
	v_mfma_f32_32x32x16_bf16 v[144:159], v[224:227], v[182:185], v[144:159]
	s_waitcnt lgkmcnt(2)
	v_mfma_f32_32x32x16_bf16 v[112:127], v[228:231], v[182:185], v[112:127]
	s_nop 9
	v_max_f32_e32 v160, v145, v145
	v_max_f32_e32 v215, v144, v144
	v_max_f32_e32 v160, v215, v160
	v_mfma_f32_32x32x16_bf16 v[128:143], v[224:227], v[190:193], v[128:143]
	v_max3_f32 v215, v146, v147, v113
	v_max3_f32 v160, v160, v112, v114
	v_max3_f32 v160, v160, v115, v148
	v_max3_f32 v215, v215, v150, v151
	v_max3_f32 v160, v160, v149, v116
	v_max3_f32 v215, v215, v118, v119
	v_max3_f32 v160, v160, v117, v152
	v_max3_f32 v215, v215, v154, v155
	v_max3_f32 v160, v160, v153, v120
	v_max3_f32 v215, v215, v122, v123
	v_mfma_f32_32x32x16_bf16 v[96:111], v[228:231], v[190:193], v[96:111]
	v_max3_f32 v160, v160, v121, v156
	v_max3_f32 v215, v215, v158, v159
	v_max3_f32 v160, v160, v157, v124
	v_max3_f32 v215, v215, v126, v127
	v_max3_f32 v160, v160, v125, v215
	v_mov_b32_e32 v215, v160
	s_nop 1
	v_permlane32_swap_b32_e32 v160, v215
	v_max_f32_e32 v215, v215, v215
	v_max_f32_e32 v160, v160, v160
	v_max_f32_e32 v160, v160, v215
	v_cmp_lt_f32_e32 vcc, s17, v160
	s_cbranch_vccz .LBB0_364
	v_max_f32_e32 v48, v160, v160
	v_max_f32_e32 v50, 0, v48
	v_exp_f32_e64 v51, -v50
	s_nop 0
	v_pk_add_f32 v[52:53], v[216:217], v[50:51]
	v_pk_mul_f32 v[48:49], v[216:217], v[50:51]
	v_pk_add_f32 v[144:145], v[144:145], v[50:51] op_sel_hi:[1,0] neg_lo:[0,1] neg_hi:[0,1]
	v_mov_b32_e32 v53, v49
	v_pk_add_f32 v[112:113], v[112:113], v[50:51] op_sel_hi:[1,0] neg_lo:[0,1] neg_hi:[0,1]
	v_pk_add_f32 v[48:49], v[52:53], 0 neg_lo:[1,1] neg_hi:[1,1]
	v_pk_add_f32 v[146:147], v[146:147], v[50:51] op_sel_hi:[1,0] neg_lo:[0,1] neg_hi:[0,1]
	v_pk_add_f32 v[114:115], v[114:115], v[50:51] op_sel_hi:[1,0] neg_lo:[0,1] neg_hi:[0,1]
	v_pk_add_f32 v[148:149], v[148:149], v[50:51] op_sel_hi:[1,0] neg_lo:[0,1] neg_hi:[0,1]
	v_pk_add_f32 v[116:117], v[116:117], v[50:51] op_sel_hi:[1,0] neg_lo:[0,1] neg_hi:[0,1]
	v_pk_add_f32 v[150:151], v[150:151], v[50:51] op_sel_hi:[1,0] neg_lo:[0,1] neg_hi:[0,1]
	v_pk_add_f32 v[118:119], v[118:119], v[50:51] op_sel_hi:[1,0] neg_lo:[0,1] neg_hi:[0,1]
	v_pk_add_f32 v[152:153], v[152:153], v[50:51] op_sel_hi:[1,0] neg_lo:[0,1] neg_hi:[0,1]
	v_pk_add_f32 v[120:121], v[120:121], v[50:51] op_sel_hi:[1,0] neg_lo:[0,1] neg_hi:[0,1]
	v_pk_add_f32 v[154:155], v[154:155], v[50:51] op_sel_hi:[1,0] neg_lo:[0,1] neg_hi:[0,1]
	v_pk_add_f32 v[122:123], v[122:123], v[50:51] op_sel_hi:[1,0] neg_lo:[0,1] neg_hi:[0,1]
	v_pk_add_f32 v[156:157], v[156:157], v[50:51] op_sel_hi:[1,0] neg_lo:[0,1] neg_hi:[0,1]
	v_pk_add_f32 v[124:125], v[124:125], v[50:51] op_sel_hi:[1,0] neg_lo:[0,1] neg_hi:[0,1]
	v_pk_add_f32 v[158:159], v[158:159], v[50:51] op_sel_hi:[1,0] neg_lo:[0,1] neg_hi:[0,1]
	v_pk_add_f32 v[126:127], v[126:127], v[50:51] op_sel_hi:[1,0] neg_lo:[0,1] neg_hi:[0,1]
	v_mov_b32_e32 v50, v51
	v_pk_mul_f32 v[78:79], v[78:79], v[50:51] op_sel_hi:[1,0]
	v_pk_mul_f32 v[76:77], v[76:77], v[50:51] op_sel_hi:[1,0]
	v_pk_mul_f32 v[74:75], v[74:75], v[50:51] op_sel_hi:[1,0]
	v_pk_mul_f32 v[72:73], v[72:73], v[50:51] op_sel_hi:[1,0]
	v_pk_mul_f32 v[70:71], v[70:71], v[50:51] op_sel_hi:[1,0]
	v_pk_mul_f32 v[68:69], v[68:69], v[50:51] op_sel_hi:[1,0]
	v_pk_mul_f32 v[66:67], v[66:67], v[50:51] op_sel_hi:[1,0]
	v_pk_mul_f32 v[64:65], v[64:65], v[50:51] op_sel_hi:[1,0]
	v_pk_mul_f32 v[14:15], v[14:15], v[50:51] op_sel_hi:[1,0]
	v_pk_mul_f32 v[12:13], v[12:13], v[50:51] op_sel_hi:[1,0]
	v_pk_mul_f32 v[10:11], v[10:11], v[50:51] op_sel_hi:[1,0]
	v_pk_mul_f32 v[8:9], v[8:9], v[50:51] op_sel_hi:[1,0]
	v_pk_mul_f32 v[6:7], v[6:7], v[50:51] op_sel_hi:[1,0]
	v_pk_mul_f32 v[4:5], v[4:5], v[50:51] op_sel_hi:[1,0]
	v_pk_mul_f32 v[2:3], v[2:3], v[50:51] op_sel_hi:[1,0]
	v_pk_mul_f32 v[0:1], v[0:1], v[50:51] op_sel_hi:[1,0]
	v_mov_b64_e32 v[216:217], v[52:53]
	v_mov_b32_e32 v49, v48
	v_mov_b32_e32 v50, v48
	v_mov_b32_e32 v51, v48
	v_mov_b32_e32 v52, v48
	v_mov_b32_e32 v53, v48
	v_mov_b32_e32 v54, v48
	v_mov_b32_e32 v55, v48
	v_mov_b32_e32 v56, v48
	v_mov_b32_e32 v57, v48
	v_mov_b32_e32 v58, v48
	v_mov_b32_e32 v59, v48
	v_mov_b32_e32 v60, v48
	v_mov_b32_e32 v61, v48
	v_mov_b32_e32 v62, v48
	v_mov_b32_e32 v63, v48

.LBB0_366:
	v_add3_u32 v160, s15, v211, v210
	v_add_u32_e32 v215, 0x2000, v160
	v_add_u32_e32 v160, 0x3000, v160
	v_exp_f32_e32 v144, v144
	v_exp_f32_e32 v145, v145
	v_exp_f32_e32 v146, v146
	v_exp_f32_e32 v147, v147
	v_exp_f32_e32 v148, v148
	v_exp_f32_e32 v149, v149
	v_exp_f32_e32 v150, v150
	v_exp_f32_e32 v151, v151
	v_exp_f32_e32 v228, v128
	v_exp_f32_e32 v229, v129
	v_exp_f32_e32 v226, v130
	v_exp_f32_e32 v227, v131
	v_exp_f32_e32 v224, v132
	v_exp_f32_e32 v225, v133
	v_exp_f32_e32 v230, v134
	v_exp_f32_e32 v231, v135
	v_cvt_pk_bf16_f32 v240, v144, v145
	v_cvt_pk_bf16_f32 v241, v146, v147
	v_cvt_pk_bf16_f32 v242, v148, v149
	v_cvt_pk_bf16_f32 v243, v150, v151
	v_exp_f32_e32 v132, v152
	v_exp_f32_e32 v133, v153
	s_waitcnt lgkmcnt(1)
	v_mfma_f32_32x32x16_bf16 v[64:79], v[232:235], v[240:243], v[64:79]
	v_exp_f32_e32 v130, v154
	v_exp_f32_e32 v131, v155
	v_exp_f32_e32 v128, v156
	v_exp_f32_e32 v129, v157
	v_exp_f32_e32 v134, v158
	v_exp_f32_e32 v135, v159
	v_exp_f32_e32 v152, v136
	s_waitcnt lgkmcnt(0)
	v_mfma_f32_32x32x16_bf16 v[0:15], v[248:251], v[240:243], v[0:15]
	v_cvt_pk_bf16_f32 v240, v228, v229
	v_cvt_pk_bf16_f32 v241, v226, v227
	v_cvt_pk_bf16_f32 v242, v224, v225
	v_cvt_pk_bf16_f32 v243, v230, v231
	v_exp_f32_e32 v153, v137
	v_exp_f32_e32 v138, v138
	v_exp_f32_e32 v139, v139
	v_mfma_f32_32x32x16_bf16 v[32:47], v[232:235], v[240:243], v[32:47]
	ds_read2_b64 v[232:235], v215 offset0:132 offset1:134
	v_exp_f32_e32 v136, v140
	v_exp_f32_e32 v137, v141
	v_exp_f32_e32 v140, v142
	v_exp_f32_e32 v141, v143
	v_cvt_pk_bf16_f32 v154, v132, v133
	v_cvt_pk_bf16_f32 v155, v130, v131
	v_mfma_f32_32x32x16_bf16 v[16:31], v[248:251], v[240:243], v[16:31]
	ds_read2_b64 v[240:243], v160 offset0:164 offset1:166
	v_cvt_pk_bf16_f32 v156, v128, v129
	v_cvt_pk_bf16_f32 v157, v134, v135
	v_exp_f32_e32 v142, v112
	v_exp_f32_e32 v143, v113
	v_exp_f32_e32 v114, v114
	v_exp_f32_e32 v115, v115
	s_waitcnt lgkmcnt(1)
	v_mfma_f32_32x32x16_bf16 v[64:79], v[232:235], v[154:157], v[64:79]
	v_exp_f32_e32 v112, v116
	v_exp_f32_e32 v113, v117
	v_exp_f32_e32 v116, v118
	v_exp_f32_e32 v117, v119
	v_exp_f32_e32 v118, v98
	v_cvt_pk_bf16_f32 v158, v112, v113
	v_exp_f32_e32 v119, v99
	s_waitcnt lgkmcnt(0)
	v_mfma_f32_32x32x16_bf16 v[0:15], v[240:243], v[154:157], v[0:15]
	v_cvt_pk_bf16_f32 v154, v152, v153
	v_cvt_pk_bf16_f32 v155, v138, v139
	v_cvt_pk_bf16_f32 v156, v136, v137
	v_cvt_pk_bf16_f32 v157, v140, v141
	v_cvt_pk_bf16_f32 v159, v116, v117
	v_cvt_pk_bf16_f32 v249, v118, v119
	v_exp_f32_e32 v98, v124
	v_mfma_f32_32x32x16_bf16 v[32:47], v[232:235], v[154:157], v[32:47]
	ds_read2_b64 v[232:235], v215 offset0:136 offset1:138
	v_exp_f32_e32 v99, v125
	v_exp_f32_e32 v106, v106
	v_exp_f32_e32 v107, v107
	s_andn2_b64 vcc, exec, s[2:3]
	v_mfma_f32_32x32x16_bf16 v[16:31], v[240:243], v[154:157], v[16:31]
	ds_read2_b64 v[240:243], v160 offset0:168 offset1:170
	v_cvt_pk_bf16_f32 v156, v142, v143
	v_cvt_pk_bf16_f32 v157, v114, v115
	v_exp_f32_e32 v154, v96
	v_exp_f32_e32 v155, v97
	v_exp_f32_e32 v96, v100
	v_exp_f32_e32 v97, v101
	s_waitcnt lgkmcnt(1)
	v_mfma_f32_32x32x16_bf16 v[64:79], v[232:235], v[156:159], v[64:79]
	v_cvt_pk_bf16_f32 v248, v154, v155
	v_exp_f32_e32 v100, v122
	v_cvt_pk_bf16_f32 v250, v96, v97
	v_exp_f32_e32 v101, v123
	v_exp_f32_e32 v122, v104
	v_exp_f32_e32 v123, v105
	v_exp_f32_e32 v104, v108
	s_waitcnt lgkmcnt(0)
	v_mfma_f32_32x32x16_bf16 v[0:15], v[240:243], v[156:159], v[0:15]
	v_exp_f32_e32 v156, v102
	v_exp_f32_e32 v157, v103
	v_exp_f32_e32 v102, v120
	v_exp_f32_e32 v103, v121
	v_exp_f32_e32 v120, v126
	v_cvt_pk_bf16_f32 v251, v156, v157
	v_exp_f32_e32 v121, v127
	v_exp_f32_e32 v105, v109
	v_mfma_f32_32x32x16_bf16 v[32:47], v[232:235], v[248:251], v[32:47]
	ds_read2_b64 v[232:235], v215 offset0:140 offset1:142
	v_exp_f32_e32 v108, v110
	v_exp_f32_e32 v109, v111
	v_cvt_pk_bf16_f32 v124, v102, v103
	v_cvt_pk_bf16_f32 v125, v100, v101
	v_cvt_pk_bf16_f32 v126, v98, v99
	v_cvt_pk_bf16_f32 v127, v120, v121
	v_mfma_f32_32x32x16_bf16 v[16:31], v[240:243], v[248:251], v[16:31]
	ds_read2_b64 v[240:243], v160 offset0:172 offset1:174
	s_waitcnt lgkmcnt(1)
	v_mfma_f32_32x32x16_bf16 v[64:79], v[232:235], v[124:127], v[64:79]
	s_waitcnt lgkmcnt(0)
	v_mfma_f32_32x32x16_bf16 v[0:15], v[240:243], v[124:127], v[0:15]
	v_cvt_pk_bf16_f32 v124, v122, v123
	v_cvt_pk_bf16_f32 v125, v106, v107
	v_cvt_pk_bf16_f32 v126, v104, v105
	v_cvt_pk_bf16_f32 v127, v108, v109
	s_nop 1
	v_mfma_f32_32x32x16_bf16 v[32:47], v[232:235], v[124:127], v[32:47]
	v_mfma_f32_32x32x16_bf16 v[16:31], v[240:243], v[124:127], v[16:31]
	s_cbranch_vccnz .LBB0_368
	s_xor_b32 s2, s14, 1
	s_mulk_i32 s2, 0x4600
	s_add_i32 s2, s2, 16
	v_add3_u32 v110, s2, v202, v208
	v_add_u32_e32 v111, s2, v203
	s_movk_i32 s2, 0x2400
	v_add3_u32 v111, v111, v208, s2
	s_waitcnt vmcnt(1)
	ds_write_b128 v110, v[194:197]
	s_waitcnt vmcnt(0)
	ds_write2_b64 v111, v[198:199], v[200:201] offset1:1
.LBB0_368:
	s_add_i32 s11, s11, 1
	v_lshl_add_u64 v[218:219], v[218:219], 0, s[84:85]
	v_lshl_add_u64 v[220:221], v[220:221], 0, 64
	v_pk_add_f32 v[110:111], v[228:229], 0 op_sel_hi:[1,0]
	v_pk_add_f32 v[232:233], v[144:145], 0 op_sel_hi:[1,0]
	v_pk_add_f32 v[110:111], v[154:155], v[110:111]
	v_pk_add_f32 v[232:233], v[142:143], v[232:233]
	v_pk_add_f32 v[110:111], v[226:227], v[110:111]
	v_pk_add_f32 v[232:233], v[146:147], v[232:233]
	s_waitcnt lgkmcnt(0)
	s_barrier
	v_pk_add_f32 v[110:111], v[118:119], v[110:111]
	v_pk_add_f32 v[232:233], v[114:115], v[232:233]
	v_pk_add_f32 v[110:111], v[224:225], v[110:111]
	v_pk_add_f32 v[232:233], v[148:149], v[232:233]
	v_pk_add_f32 v[96:97], v[96:97], v[110:111]
	v_pk_add_f32 v[232:233], v[112:113], v[232:233]
	v_pk_add_f32 v[96:97], v[230:231], v[96:97]
	v_pk_add_f32 v[232:233], v[150:151], v[232:233]
	v_pk_add_f32 v[96:97], v[156:157], v[96:97]
	v_pk_add_f32 v[232:233], v[116:117], v[232:233]
	v_pk_add_f32 v[96:97], v[152:153], v[96:97]
	v_pk_add_f32 v[232:233], v[132:133], v[232:233]
	v_pk_add_f32 v[96:97], v[122:123], v[96:97]
	v_pk_add_f32 v[102:103], v[102:103], v[232:233]
	v_pk_add_f32 v[96:97], v[138:139], v[96:97]
	v_pk_add_f32 v[102:103], v[130:131], v[102:103]
	v_pk_add_f32 v[96:97], v[106:107], v[96:97]
	v_pk_add_f32 v[100:101], v[100:101], v[102:103]
	v_pk_add_f32 v[96:97], v[136:137], v[96:97]
	v_pk_add_f32 v[100:101], v[128:129], v[100:101]
	v_pk_add_f32 v[96:97], v[104:105], v[96:97]
	v_pk_add_f32 v[98:99], v[98:99], v[100:101]
	v_pk_add_f32 v[96:97], v[140:141], v[96:97]
	v_pk_add_f32 v[98:99], v[134:135], v[98:99]
	v_pk_add_f32 v[96:97], v[108:109], v[96:97]
	v_pk_add_f32 v[98:99], v[120:121], v[98:99]
	v_pk_add_f32 v[96:97], v[96:97], v[96:97] op_sel:[0,1] op_sel_hi:[1,0]
	v_pk_add_f32 v[98:99], v[98:99], v[98:99] op_sel:[0,1] op_sel_hi:[1,0]
	v_pk_add_f32 v[96:97], v[222:223], v[96:97] op_sel:[1,0] op_sel_hi:[0,1]
	v_pk_add_f32 v[98:99], v[216:217], v[98:99] op_sel:[1,0] op_sel_hi:[0,1]
	s_cmp_lg_u32 s11, 36
	s_cbranch_scc0 .LBB0_370
	v_mov_b32_e32 v223, v96
	v_mov_b32_e32 v217, v98
	s_cmp_lt_u32 s11, 35
	s_cselect_b64 s[2:3], -1, 0
	s_cmp_gt_u32 s11, 34
	s_cbranch_scc0 .LBB0_361
	s_branch .LBB0_362
